# attention band-skip steps no longer load K tiles beyond the unit (and skip the V load once past the last real tile)
# baseline (speedup 1.0000x reference)
.Lat_lite2_443:
	s_add_u32 s60, s46, 1
	s_cmp_lt_u32 s60, s45
	s_cbranch_scc0 .Lat_lite3_443
	s_lshl_b32 s60, s58, 1
	s_add_i32 s60, s60, s71
	s_mov_b32 m0, s60
	s_nop 0
	global_load_lds_dwordx4 v239, s[76:77]
	s_add_u32 s62, s76, 0x80
	s_addc_u32 s63, s77, 0
	s_add_i32 m0, s60, 0x2000
	s_nop 0
	global_load_lds_dwordx4 v239, s[62:63]
	s_add_u32 s76, s76, 0x10000
	s_addc_u32 s77, s77, 0
	s_waitcnt vmcnt(2) lgkmcnt(0)
	s_barrier
	s_branch .Lat_lite4_443
.Lat_lite3_443:
	s_waitcnt vmcnt(0) lgkmcnt(0)
	s_barrier
.Lat_lite4_443:
	s_mov_b32 s67, s56
	s_mov_b32 s56, s57
	s_mov_b32 s57, s58
	s_mov_b32 s58, s67
	s_add_u32 s46, s46, 1
	s_branch .Lat_next_443
